# plus attention epilogue row-sum butterflies via DPP (quad_perm, half_mirror, mirror)
# speedup vs baseline: 1.0051x; 1.0007x over previous
.LBB0_836:
	s_or_b64 exec, exec, s[0:1]
	s_waitcnt lgkmcnt(0)
	ds_read_b128 v[66:69], v174
	ds_read_b128 v[70:73], v174 offset:32
	s_lshl_b64 s[0:1], s[44:45], 11
	s_add_u32 s0, s20, s0
	s_addc_u32 s1, s21, s1
	s_lshl_b32 s4, s8, 1
	s_add_u32 s22, s0, s4
	s_waitcnt lgkmcnt(1)
	v_rcp_f32_e32 v74, v66
	s_addc_u32 s23, s1, 0
	s_lshl_b64 s[0:1], s[44:45], 4
	v_readlane_b32 s8, v251, 58
	v_readlane_b32 s9, v251, 59
	s_add_u32 s0, s8, s0
	s_addc_u32 s1, s9, s1
	s_lshl_b32 s2, s2, 2
	s_add_u32 s0, s0, s2
	v_lshl_add_u32 v82, v157, 13, 0
	v_mul_f32_e32 v2, v2, v74
	v_lshlrev_b32_e32 v83, 10, v169
	v_lshlrev_b32_e32 v84, 1, v168
	v_cvt_pk_bf16_f32 v2, v2, s0
	v_add3_u32 v83, v82, v83, v84
	v_rcp_f32_e32 v75, v67
	v_rcp_f32_e32 v76, v68
	v_rcp_f32_e32 v77, v69
	s_waitcnt lgkmcnt(0)
	v_rcp_f32_e32 v78, v70
	ds_read_b128 v[66:69], v174 offset:64
	v_rcp_f32_e32 v79, v71
	v_rcp_f32_e32 v80, v72
	v_rcp_f32_e32 v81, v73
	ds_read_b128 v[70:73], v174 offset:96
	s_waitcnt lgkmcnt(0)
	s_barrier
	ds_write_b16 v83, v2
	v_mul_f32_e32 v2, v18, v74
	v_cvt_pk_bf16_f32 v2, v2, s0
	ds_write_b16 v83, v2 offset:64
	v_mul_f32_e32 v2, v34, v74
	v_cvt_pk_bf16_f32 v2, v2, s0
	ds_write_b16 v83, v2 offset:128
	v_mul_f32_e32 v2, v50, v74
	v_cvt_pk_bf16_f32 v2, v2, s0
	ds_write_b16 v83, v2 offset:192
	v_mul_f32_e32 v2, v3, v75
	v_cvt_pk_bf16_f32 v2, v2, s0
	ds_write_b16 v83, v2 offset:256
	v_mul_f32_e32 v2, v19, v75
	v_cvt_pk_bf16_f32 v2, v2, s0
	ds_write_b16 v83, v2 offset:320
	v_mul_f32_e32 v2, v35, v75
	v_cvt_pk_bf16_f32 v2, v2, s0
	ds_write_b16 v83, v2 offset:384
	v_mul_f32_e32 v2, v51, v75
	v_cvt_pk_bf16_f32 v2, v2, s0
	ds_write_b16 v83, v2 offset:448
	v_mul_f32_e32 v2, v4, v76
	v_cvt_pk_bf16_f32 v2, v2, s0
	ds_write_b16 v83, v2 offset:512
	v_mul_f32_e32 v2, v20, v76
	v_cvt_pk_bf16_f32 v2, v2, s0
	ds_write_b16 v83, v2 offset:576
	v_mul_f32_e32 v2, v36, v76
	v_cvt_pk_bf16_f32 v2, v2, s0
	ds_write_b16 v83, v2 offset:640
	v_mul_f32_e32 v2, v52, v76
	v_cvt_pk_bf16_f32 v2, v2, s0
	ds_write_b16 v83, v2 offset:704
	v_mul_f32_e32 v2, v5, v77
	v_cvt_pk_bf16_f32 v2, v2, s0
	ds_write_b16 v83, v2 offset:768
	v_mul_f32_e32 v2, v21, v77
	v_cvt_pk_bf16_f32 v2, v2, s0
	ds_write_b16 v83, v2 offset:832
	v_mul_f32_e32 v2, v37, v77
	v_cvt_pk_bf16_f32 v2, v2, s0
	ds_write_b16 v83, v2 offset:896
	v_mul_f32_e32 v2, v53, v77
	v_cvt_pk_bf16_f32 v2, v2, s0
	ds_write_b16 v83, v2 offset:960
	v_mul_f32_e32 v2, v6, v78
	v_cvt_pk_bf16_f32 v2, v2, s0
	ds_write_b16 v83, v2 offset:2048
	v_mul_f32_e32 v2, v22, v78
	v_cvt_pk_bf16_f32 v2, v2, s0
	ds_write_b16 v83, v2 offset:2112
	v_mul_f32_e32 v2, v38, v78
	v_cvt_pk_bf16_f32 v2, v2, s0
	ds_write_b16 v83, v2 offset:2176
	v_mul_f32_e32 v2, v54, v78
	v_cvt_pk_bf16_f32 v2, v2, s0
	ds_write_b16 v83, v2 offset:2240
	v_mul_f32_e32 v2, v7, v79
	v_cvt_pk_bf16_f32 v2, v2, s0
	ds_write_b16 v83, v2 offset:2304
	v_mul_f32_e32 v2, v23, v79
	v_cvt_pk_bf16_f32 v2, v2, s0
	ds_write_b16 v83, v2 offset:2368
	v_mul_f32_e32 v2, v39, v79
	v_cvt_pk_bf16_f32 v2, v2, s0
	ds_write_b16 v83, v2 offset:2432
	v_mul_f32_e32 v2, v55, v79
	v_cvt_pk_bf16_f32 v2, v2, s0
	ds_write_b16 v83, v2 offset:2496
	v_mul_f32_e32 v2, v8, v80
	v_cvt_pk_bf16_f32 v2, v2, s0
	ds_write_b16 v83, v2 offset:2560
	v_mul_f32_e32 v2, v24, v80
	v_cvt_pk_bf16_f32 v2, v2, s0
	ds_write_b16 v83, v2 offset:2624
	v_mul_f32_e32 v2, v40, v80
	v_cvt_pk_bf16_f32 v2, v2, s0
	ds_write_b16 v83, v2 offset:2688
	v_mul_f32_e32 v2, v56, v80
	v_cvt_pk_bf16_f32 v2, v2, s0
	ds_write_b16 v83, v2 offset:2752
	v_mul_f32_e32 v2, v9, v81
	v_cvt_pk_bf16_f32 v2, v2, s0
	ds_write_b16 v83, v2 offset:2816
	v_mul_f32_e32 v2, v25, v81
	v_cvt_pk_bf16_f32 v2, v2, s0
	v_rcp_f32_e32 v66, v66
	ds_write_b16 v83, v2 offset:2880
	v_mul_f32_e32 v2, v41, v81
	v_cvt_pk_bf16_f32 v2, v2, s0
	ds_write_b16 v83, v2 offset:2944
	v_mul_f32_e32 v2, v57, v81
	v_cvt_pk_bf16_f32 v2, v2, s0
	ds_write_b16 v83, v2 offset:3008
	v_mul_f32_e32 v2, v10, v66
	v_cvt_pk_bf16_f32 v2, v2, s0
	ds_write_b16 v83, v2 offset:4096
	v_mul_f32_e32 v2, v26, v66
	v_cvt_pk_bf16_f32 v2, v2, s0
	v_rcp_f32_e32 v67, v67
	ds_write_b16 v83, v2 offset:4160
	v_mul_f32_e32 v2, v42, v66
	v_cvt_pk_bf16_f32 v2, v2, s0
	ds_write_b16 v83, v2 offset:4224
	v_mul_f32_e32 v2, v58, v66
	v_cvt_pk_bf16_f32 v2, v2, s0
	ds_write_b16 v83, v2 offset:4288
	v_mul_f32_e32 v2, v11, v67
	v_cvt_pk_bf16_f32 v2, v2, s0
	ds_write_b16 v83, v2 offset:4352
	v_mul_f32_e32 v2, v27, v67
	v_cvt_pk_bf16_f32 v2, v2, s0
	v_rcp_f32_e32 v68, v68
	ds_write_b16 v83, v2 offset:4416
	v_mul_f32_e32 v2, v43, v67
	v_cvt_pk_bf16_f32 v2, v2, s0
	ds_write_b16 v83, v2 offset:4480
	v_mul_f32_e32 v2, v59, v67
	v_cvt_pk_bf16_f32 v2, v2, s0
	ds_write_b16 v83, v2 offset:4544
	v_mul_f32_e32 v2, v12, v68
	v_cvt_pk_bf16_f32 v2, v2, s0
	ds_write_b16 v83, v2 offset:4608
	v_mul_f32_e32 v2, v28, v68
	v_cvt_pk_bf16_f32 v2, v2, s0
	v_rcp_f32_e32 v69, v69
	ds_write_b16 v83, v2 offset:4672
	v_mul_f32_e32 v2, v44, v68
	v_cvt_pk_bf16_f32 v2, v2, s0
	ds_write_b16 v83, v2 offset:4736
	v_mul_f32_e32 v2, v60, v68
	v_cvt_pk_bf16_f32 v2, v2, s0
	ds_write_b16 v83, v2 offset:4800
	v_mul_f32_e32 v2, v13, v69
	v_cvt_pk_bf16_f32 v2, v2, s0
	ds_write_b16 v83, v2 offset:4864
	v_mul_f32_e32 v2, v29, v69
	v_cvt_pk_bf16_f32 v2, v2, s0
	v_rcp_f32_e32 v70, v70
	ds_write_b16 v83, v2 offset:4928
	v_mul_f32_e32 v2, v45, v69
	v_cvt_pk_bf16_f32 v2, v2, s0
	ds_write_b16 v83, v2 offset:4992
	v_mul_f32_e32 v2, v61, v69
	v_cvt_pk_bf16_f32 v2, v2, s0
	ds_write_b16 v83, v2 offset:5056
	v_mul_f32_e32 v2, v14, v70
	v_cvt_pk_bf16_f32 v2, v2, s0
	ds_write_b16 v83, v2 offset:6144
	v_mul_f32_e32 v2, v30, v70
	v_cvt_pk_bf16_f32 v2, v2, s0
	v_rcp_f32_e32 v71, v71
	ds_write_b16 v83, v2 offset:6208
	v_mul_f32_e32 v2, v46, v70
	v_cvt_pk_bf16_f32 v2, v2, s0
	ds_write_b16 v83, v2 offset:6272
	v_mul_f32_e32 v2, v62, v70
	v_cvt_pk_bf16_f32 v2, v2, s0
	ds_write_b16 v83, v2 offset:6336
	v_mul_f32_e32 v2, v15, v71
	v_cvt_pk_bf16_f32 v2, v2, s0
	ds_write_b16 v83, v2 offset:6400
	v_mul_f32_e32 v2, v31, v71
	v_cvt_pk_bf16_f32 v2, v2, s0
	v_rcp_f32_e32 v72, v72
	ds_write_b16 v83, v2 offset:6464
	v_mul_f32_e32 v2, v47, v71
	v_cvt_pk_bf16_f32 v2, v2, s0
	ds_write_b16 v83, v2 offset:6528
	v_mul_f32_e32 v2, v63, v71
	v_cvt_pk_bf16_f32 v2, v2, s0
	ds_write_b16 v83, v2 offset:6592
	v_mul_f32_e32 v2, v16, v72
	v_cvt_pk_bf16_f32 v2, v2, s0
	ds_write_b16 v83, v2 offset:6656
	v_mul_f32_e32 v2, v32, v72
	v_cvt_pk_bf16_f32 v2, v2, s0
	v_rcp_f32_e32 v73, v73
	ds_write_b16 v83, v2 offset:6720
	v_mul_f32_e32 v2, v48, v72
	v_cvt_pk_bf16_f32 v2, v2, s0
	ds_write_b16 v83, v2 offset:6784
	v_mul_f32_e32 v2, v64, v72
	v_cvt_pk_bf16_f32 v2, v2, s0
	ds_write_b16 v83, v2 offset:6848
	v_mul_f32_e32 v2, v17, v73
	v_cvt_pk_bf16_f32 v2, v2, s0
	ds_write_b16 v83, v2 offset:6912
	v_mul_f32_e32 v2, v33, v73
	v_cvt_pk_bf16_f32 v2, v2, s0
	ds_write_b16 v83, v2 offset:6976
	v_mul_f32_e32 v2, v49, v73
	v_cvt_pk_bf16_f32 v2, v2, s0
	ds_write_b16 v83, v2 offset:7040
	v_mul_f32_e32 v2, v65, v73
	v_and_b32_e32 v16, 15, v166
	v_cvt_pk_bf16_f32 v2, v2, s0
	v_lshlrev_b32_e32 v98, 4, v16
	ds_write_b16 v83, v2 offset:7104
	v_lshrrev_b32_e32 v5, 4, v167
	v_add_u32_e32 v6, v82, v98
	s_waitcnt lgkmcnt(0)
	v_lshl_add_u32 v8, v5, 8, v6
	ds_read_b128 v[12:15], v8
	v_and_b32_e32 v7, 64, v1
	v_add_u32_e32 v9, 64, v7
	v_xor_b32_e32 v4, 1, v1
	v_cmp_lt_i32_e32 vcc, v4, v9
	s_waitcnt lgkmcnt(0)
	v_and_b32_e32 v8, 0xffff0000, v12
	v_lshlrev_b32_e32 v7, 16, v12
	v_and_b32_e32 v11, 0xffff0000, v13
	v_mul_f32_e32 v8, v8, v8
	v_lshlrev_b32_e32 v10, 16, v13
	v_fmac_f32_e32 v8, v7, v7
	v_mul_f32_e32 v7, v11, v11
	v_and_b32_e32 v18, 0xffff0000, v14
	v_and_b32_e32 v20, 0xffff0000, v15
	v_fmac_f32_e32 v7, v10, v10
	v_lshlrev_b32_e32 v17, 16, v14
	v_lshlrev_b32_e32 v19, 16, v15
	v_add_f32_e32 v7, v8, v7
	v_mul_f32_e32 v8, v18, v18
	v_mul_f32_e32 v10, v20, v20
	v_fmac_f32_e32 v8, v17, v17
	v_fmac_f32_e32 v10, v19, v19
	v_cndmask_b32_e32 v4, v1, v4, vcc
	v_add_f32_e32 v8, v8, v10
	v_lshlrev_b32_e32 v4, 2, v4
	v_add_f32_e32 v8, v7, v8
	s_nop 1
	v_mov_b32_dpp v10, v8 quad_perm:[1,0,3,2] row_mask:0xf bank_mask:0xf
	v_xor_b32_e32 v7, 2, v1
	v_cmp_lt_i32_e32 vcc, v7, v9
	v_xor_b32_e32 v17, 8, v1
	v_ashrrev_i32_e32 v157, 31, v156
	v_cndmask_b32_e32 v7, v1, v7, vcc
	v_lshlrev_b32_e32 v7, 2, v7
	s_waitcnt lgkmcnt(0)
	v_add_f32_e32 v10, v8, v10
	s_nop 1
	v_mov_b32_dpp v11, v10 quad_perm:[2,3,0,1] row_mask:0xf bank_mask:0xf
	v_xor_b32_e32 v8, 4, v1
	v_cmp_lt_i32_e32 vcc, v8, v9
	v_lshlrev_b64 v[2:3], 11, v[156:157]
	v_lshl_add_u64 v[2:3], s[22:23], 0, v[2:3]
	v_cndmask_b32_e32 v8, v1, v8, vcc
	v_lshlrev_b32_e32 v8, 2, v8
	s_waitcnt lgkmcnt(0)
	v_add_f32_e32 v10, v10, v11
	s_nop 1
	v_mov_b32_dpp v11, v10 row_half_mirror row_mask:0xf bank_mask:0xf
	v_cmp_lt_i32_e32 vcc, v17, v9
	v_lshl_add_u64 v[2:3], v[2:3], 0, v[98:99]
	v_lshlrev_b32_e32 v98, 11, v5
	v_cndmask_b32_e32 v9, v1, v17, vcc
	v_lshlrev_b32_e32 v9, 2, v9
	s_waitcnt lgkmcnt(0)
	v_add_f32_e32 v10, v10, v11
	s_nop 1
	v_mov_b32_dpp v11, v10 row_mirror row_mask:0xf bank_mask:0xf
	s_addc_u32 s1, s1, 0
	v_cmp_eq_u32_e32 vcc, 0, v16
	v_lshl_add_u64 v[16:17], v[2:3], 0, v[98:99]
	global_store_dwordx4 v[16:17], v[12:15], off
	s_and_saveexec_b64 s[22:23], vcc
	s_cbranch_execz .LBB0_838
	s_waitcnt lgkmcnt(0)
	v_add_f32_e32 v12, v10, v11
	v_or_b32_e32 v10, v5, v156
	v_lshlrev_b32_e32 v10, 2, v10
	v_ashrrev_i32_e32 v11, 31, v10
	v_lshl_add_u64 v[10:11], v[10:11], 2, s[0:1]
	global_store_dword v[10:11], v12, off
.LBB0_838:
	s_or_b64 exec, exec, s[22:23]
	v_or_b32_e32 v10, 4, v5
	s_waitcnt lgkmcnt(0)
	v_lshl_add_u32 v11, v10, 8, v6
	ds_read_b128 v[12:15], v11
	v_lshlrev_b32_e32 v98, 11, v10
	v_lshl_add_u64 v[16:17], v[2:3], 0, v[98:99]
	s_waitcnt lgkmcnt(0)
	global_store_dwordx4 v[16:17], v[12:15], off
	v_lshlrev_b32_e32 v11, 16, v12
	s_nop 0
	v_and_b32_e32 v12, 0xffff0000, v12
	v_lshlrev_b32_e32 v16, 16, v13
	v_and_b32_e32 v13, 0xffff0000, v13
	v_mul_f32_e32 v12, v12, v12
	v_fmac_f32_e32 v12, v11, v11
	v_mul_f32_e32 v11, v13, v13
	v_lshlrev_b32_e32 v17, 16, v14
	v_and_b32_e32 v14, 0xffff0000, v14
	v_lshlrev_b32_e32 v18, 16, v15
	v_and_b32_e32 v15, 0xffff0000, v15
	v_fmac_f32_e32 v11, v16, v16
	v_add_f32_e32 v11, v12, v11
	v_mul_f32_e32 v12, v14, v14
	v_mul_f32_e32 v13, v15, v15
	v_fmac_f32_e32 v12, v17, v17
	v_fmac_f32_e32 v13, v18, v18
	v_add_f32_e32 v12, v12, v13
	v_add_f32_e32 v11, v11, v12
	s_nop 1
	v_mov_b32_dpp v12, v11 quad_perm:[1,0,3,2] row_mask:0xf bank_mask:0xf
	s_waitcnt lgkmcnt(0)
	v_add_f32_e32 v11, v11, v12
	s_nop 1
	v_mov_b32_dpp v12, v11 quad_perm:[2,3,0,1] row_mask:0xf bank_mask:0xf
	s_waitcnt lgkmcnt(0)
	v_add_f32_e32 v11, v11, v12
	s_nop 1
	v_mov_b32_dpp v12, v11 row_half_mirror row_mask:0xf bank_mask:0xf
	s_waitcnt lgkmcnt(0)
	v_add_f32_e32 v11, v11, v12
	s_nop 1
	v_mov_b32_dpp v12, v11 row_mirror row_mask:0xf bank_mask:0xf
	s_and_saveexec_b64 s[22:23], vcc
	s_cbranch_execz .LBB0_840
	v_or_b32_e32 v10, v10, v156
	v_lshlrev_b32_e32 v10, 2, v10
	s_waitcnt lgkmcnt(0)
	v_add_f32_e32 v12, v11, v12
	v_ashrrev_i32_e32 v11, 31, v10
	v_lshl_add_u64 v[10:11], v[10:11], 2, s[0:1]
	global_store_dword v[10:11], v12, off
.LBB0_840:
	s_or_b64 exec, exec, s[22:23]
	v_or_b32_e32 v10, 8, v5
	v_lshl_add_u32 v11, v10, 8, v6
	s_waitcnt lgkmcnt(0)
	ds_read_b128 v[12:15], v11
	v_lshlrev_b32_e32 v98, 11, v10
	v_lshl_add_u64 v[16:17], v[2:3], 0, v[98:99]
	s_waitcnt lgkmcnt(0)
	global_store_dwordx4 v[16:17], v[12:15], off
	v_lshlrev_b32_e32 v11, 16, v12
	s_nop 0
	v_and_b32_e32 v12, 0xffff0000, v12
	v_lshlrev_b32_e32 v16, 16, v13
	v_and_b32_e32 v13, 0xffff0000, v13
	v_mul_f32_e32 v12, v12, v12
	v_fmac_f32_e32 v12, v11, v11
	v_mul_f32_e32 v11, v13, v13
	v_lshlrev_b32_e32 v17, 16, v14
	v_and_b32_e32 v14, 0xffff0000, v14
	v_lshlrev_b32_e32 v18, 16, v15
	v_and_b32_e32 v15, 0xffff0000, v15
	v_fmac_f32_e32 v11, v16, v16
	v_add_f32_e32 v11, v12, v11
	v_mul_f32_e32 v12, v14, v14
	v_mul_f32_e32 v13, v15, v15
	v_fmac_f32_e32 v12, v17, v17
	v_fmac_f32_e32 v13, v18, v18
	v_add_f32_e32 v12, v12, v13
	v_add_f32_e32 v11, v11, v12
	s_nop 1
	v_mov_b32_dpp v12, v11 quad_perm:[1,0,3,2] row_mask:0xf bank_mask:0xf
	s_waitcnt lgkmcnt(0)
	v_add_f32_e32 v11, v11, v12
	s_nop 1
	v_mov_b32_dpp v12, v11 quad_perm:[2,3,0,1] row_mask:0xf bank_mask:0xf
	s_waitcnt lgkmcnt(0)
	v_add_f32_e32 v11, v11, v12
	s_nop 1
	v_mov_b32_dpp v12, v11 row_half_mirror row_mask:0xf bank_mask:0xf
	s_waitcnt lgkmcnt(0)
	v_add_f32_e32 v11, v11, v12
	s_nop 1
	v_mov_b32_dpp v12, v11 row_mirror row_mask:0xf bank_mask:0xf
	s_and_saveexec_b64 s[22:23], vcc
	s_cbranch_execz .LBB0_842
	v_or_b32_e32 v10, v10, v156
	v_lshlrev_b32_e32 v10, 2, v10
	s_waitcnt lgkmcnt(0)
	v_add_f32_e32 v12, v11, v12
	v_ashrrev_i32_e32 v11, 31, v10
	v_lshl_add_u64 v[10:11], v[10:11], 2, s[0:1]
	global_store_dword v[10:11], v12, off
.LBB0_842:
	s_or_b64 exec, exec, s[22:23]
	v_or_b32_e32 v10, 12, v5
	v_lshl_add_u32 v11, v10, 8, v6
	s_waitcnt lgkmcnt(0)
	ds_read_b128 v[12:15], v11
	v_lshlrev_b32_e32 v98, 11, v10
	v_lshl_add_u64 v[16:17], v[2:3], 0, v[98:99]
	s_waitcnt lgkmcnt(0)
	global_store_dwordx4 v[16:17], v[12:15], off
	v_lshlrev_b32_e32 v11, 16, v12
	s_nop 0
	v_and_b32_e32 v12, 0xffff0000, v12
	v_lshlrev_b32_e32 v16, 16, v13
	v_and_b32_e32 v13, 0xffff0000, v13
	v_mul_f32_e32 v12, v12, v12
	v_fmac_f32_e32 v12, v11, v11
	v_mul_f32_e32 v11, v13, v13
	v_lshlrev_b32_e32 v17, 16, v14
	v_and_b32_e32 v14, 0xffff0000, v14
	v_lshlrev_b32_e32 v18, 16, v15
	v_and_b32_e32 v15, 0xffff0000, v15
	v_fmac_f32_e32 v11, v16, v16
	v_add_f32_e32 v11, v12, v11
	v_mul_f32_e32 v12, v14, v14
	v_mul_f32_e32 v13, v15, v15
	v_fmac_f32_e32 v12, v17, v17
	v_fmac_f32_e32 v13, v18, v18
	v_add_f32_e32 v12, v12, v13
	v_add_f32_e32 v11, v11, v12
	s_nop 1
	v_mov_b32_dpp v12, v11 quad_perm:[1,0,3,2] row_mask:0xf bank_mask:0xf
	s_waitcnt lgkmcnt(0)
	v_add_f32_e32 v11, v11, v12
	s_nop 1
	v_mov_b32_dpp v12, v11 quad_perm:[2,3,0,1] row_mask:0xf bank_mask:0xf
	s_waitcnt lgkmcnt(0)
	v_add_f32_e32 v11, v11, v12
	s_nop 1
	v_mov_b32_dpp v12, v11 row_half_mirror row_mask:0xf bank_mask:0xf
	s_waitcnt lgkmcnt(0)
	v_add_f32_e32 v11, v11, v12
	s_nop 1
	v_mov_b32_dpp v12, v11 row_mirror row_mask:0xf bank_mask:0xf
	s_and_saveexec_b64 s[22:23], vcc
	s_cbranch_execz .LBB0_844
	v_or_b32_e32 v10, v10, v156
	v_lshlrev_b32_e32 v10, 2, v10
	s_waitcnt lgkmcnt(0)
	v_add_f32_e32 v12, v11, v12
	v_ashrrev_i32_e32 v11, 31, v10
	v_lshl_add_u64 v[10:11], v[10:11], 2, s[0:1]
	global_store_dword v[10:11], v12, off
.LBB0_844:
	s_or_b64 exec, exec, s[22:23]
	v_or_b32_e32 v10, 16, v5
	v_lshl_add_u32 v11, v10, 8, v6
	s_waitcnt lgkmcnt(0)
	ds_read_b128 v[12:15], v11
	v_lshlrev_b32_e32 v98, 11, v10
	v_lshl_add_u64 v[16:17], v[2:3], 0, v[98:99]
	s_waitcnt lgkmcnt(0)
	global_store_dwordx4 v[16:17], v[12:15], off
	v_lshlrev_b32_e32 v11, 16, v12
	s_nop 0
	v_and_b32_e32 v12, 0xffff0000, v12
	v_lshlrev_b32_e32 v16, 16, v13
	v_and_b32_e32 v13, 0xffff0000, v13
	v_mul_f32_e32 v12, v12, v12
	v_fmac_f32_e32 v12, v11, v11
	v_mul_f32_e32 v11, v13, v13
	v_lshlrev_b32_e32 v17, 16, v14
	v_and_b32_e32 v14, 0xffff0000, v14
	v_lshlrev_b32_e32 v18, 16, v15
	v_and_b32_e32 v15, 0xffff0000, v15
	v_fmac_f32_e32 v11, v16, v16
	v_add_f32_e32 v11, v12, v11
	v_mul_f32_e32 v12, v14, v14
	v_mul_f32_e32 v13, v15, v15
	v_fmac_f32_e32 v12, v17, v17
	v_fmac_f32_e32 v13, v18, v18
	v_add_f32_e32 v12, v12, v13
	v_add_f32_e32 v11, v11, v12
	s_nop 1
	v_mov_b32_dpp v12, v11 quad_perm:[1,0,3,2] row_mask:0xf bank_mask:0xf
	s_waitcnt lgkmcnt(0)
	v_add_f32_e32 v11, v11, v12
	s_nop 1
	v_mov_b32_dpp v12, v11 quad_perm:[2,3,0,1] row_mask:0xf bank_mask:0xf
	s_waitcnt lgkmcnt(0)
	v_add_f32_e32 v11, v11, v12
	s_nop 1
	v_mov_b32_dpp v12, v11 row_half_mirror row_mask:0xf bank_mask:0xf
	s_waitcnt lgkmcnt(0)
	v_add_f32_e32 v11, v11, v12
	s_nop 1
	v_mov_b32_dpp v12, v11 row_mirror row_mask:0xf bank_mask:0xf
	s_and_saveexec_b64 s[22:23], vcc
	s_cbranch_execz .LBB0_846
	v_or_b32_e32 v10, v10, v156
	v_lshlrev_b32_e32 v10, 2, v10
	s_waitcnt lgkmcnt(0)
	v_add_f32_e32 v12, v11, v12
	v_ashrrev_i32_e32 v11, 31, v10
	v_lshl_add_u64 v[10:11], v[10:11], 2, s[0:1]
	global_store_dword v[10:11], v12, off
.LBB0_846:
	s_or_b64 exec, exec, s[22:23]
	v_or_b32_e32 v10, 20, v5
	v_lshl_add_u32 v11, v10, 8, v6
	s_waitcnt lgkmcnt(0)
	ds_read_b128 v[12:15], v11
	v_lshlrev_b32_e32 v98, 11, v10
	v_lshl_add_u64 v[16:17], v[2:3], 0, v[98:99]
	s_waitcnt lgkmcnt(0)
	global_store_dwordx4 v[16:17], v[12:15], off
	v_lshlrev_b32_e32 v11, 16, v12
	s_nop 0
	v_and_b32_e32 v12, 0xffff0000, v12
	v_lshlrev_b32_e32 v16, 16, v13
	v_and_b32_e32 v13, 0xffff0000, v13
	v_mul_f32_e32 v12, v12, v12
	v_fmac_f32_e32 v12, v11, v11
	v_mul_f32_e32 v11, v13, v13
	v_lshlrev_b32_e32 v17, 16, v14
	v_and_b32_e32 v14, 0xffff0000, v14
	v_lshlrev_b32_e32 v18, 16, v15
	v_and_b32_e32 v15, 0xffff0000, v15
	v_fmac_f32_e32 v11, v16, v16
	v_add_f32_e32 v11, v12, v11
	v_mul_f32_e32 v12, v14, v14
	v_mul_f32_e32 v13, v15, v15
	v_fmac_f32_e32 v12, v17, v17
	v_fmac_f32_e32 v13, v18, v18
	v_add_f32_e32 v12, v12, v13
	v_add_f32_e32 v11, v11, v12
	s_nop 1
	v_mov_b32_dpp v12, v11 quad_perm:[1,0,3,2] row_mask:0xf bank_mask:0xf
	s_waitcnt lgkmcnt(0)
	v_add_f32_e32 v11, v11, v12
	s_nop 1
	v_mov_b32_dpp v12, v11 quad_perm:[2,3,0,1] row_mask:0xf bank_mask:0xf
	s_waitcnt lgkmcnt(0)
	v_add_f32_e32 v11, v11, v12
	s_nop 1
	v_mov_b32_dpp v12, v11 row_half_mirror row_mask:0xf bank_mask:0xf
	s_waitcnt lgkmcnt(0)
	v_add_f32_e32 v11, v11, v12
	s_nop 1
	v_mov_b32_dpp v12, v11 row_mirror row_mask:0xf bank_mask:0xf
	s_and_saveexec_b64 s[22:23], vcc
	s_cbranch_execz .LBB0_848
	v_or_b32_e32 v10, v10, v156
	v_lshlrev_b32_e32 v10, 2, v10
	s_waitcnt lgkmcnt(0)
	v_add_f32_e32 v12, v11, v12
	v_ashrrev_i32_e32 v11, 31, v10
	v_lshl_add_u64 v[10:11], v[10:11], 2, s[0:1]
	global_store_dword v[10:11], v12, off
.LBB0_848:
	s_or_b64 exec, exec, s[22:23]
	v_or_b32_e32 v10, 24, v5
	v_lshl_add_u32 v11, v10, 8, v6
	s_waitcnt lgkmcnt(0)
	ds_read_b128 v[12:15], v11
	v_lshlrev_b32_e32 v98, 11, v10
	v_lshl_add_u64 v[16:17], v[2:3], 0, v[98:99]
	s_waitcnt lgkmcnt(0)
	global_store_dwordx4 v[16:17], v[12:15], off
	v_lshlrev_b32_e32 v11, 16, v12
	s_nop 0
	v_and_b32_e32 v12, 0xffff0000, v12
	v_lshlrev_b32_e32 v16, 16, v13
	v_and_b32_e32 v13, 0xffff0000, v13
	v_mul_f32_e32 v12, v12, v12
	v_fmac_f32_e32 v12, v11, v11
	v_mul_f32_e32 v11, v13, v13
	v_lshlrev_b32_e32 v17, 16, v14
	v_and_b32_e32 v14, 0xffff0000, v14
	v_lshlrev_b32_e32 v18, 16, v15
	v_and_b32_e32 v15, 0xffff0000, v15
	v_fmac_f32_e32 v11, v16, v16
	v_add_f32_e32 v11, v12, v11
	v_mul_f32_e32 v12, v14, v14
	v_mul_f32_e32 v13, v15, v15
	v_fmac_f32_e32 v12, v17, v17
	v_fmac_f32_e32 v13, v18, v18
	v_add_f32_e32 v12, v12, v13
	v_add_f32_e32 v11, v11, v12
	s_nop 1
	v_mov_b32_dpp v12, v11 quad_perm:[1,0,3,2] row_mask:0xf bank_mask:0xf
	s_waitcnt lgkmcnt(0)
	v_add_f32_e32 v11, v11, v12
	s_nop 1
	v_mov_b32_dpp v12, v11 quad_perm:[2,3,0,1] row_mask:0xf bank_mask:0xf
	s_waitcnt lgkmcnt(0)
	v_add_f32_e32 v11, v11, v12
	s_nop 1
	v_mov_b32_dpp v12, v11 row_half_mirror row_mask:0xf bank_mask:0xf
	s_waitcnt lgkmcnt(0)
	v_add_f32_e32 v11, v11, v12
	s_nop 1
	v_mov_b32_dpp v12, v11 row_mirror row_mask:0xf bank_mask:0xf
	s_and_saveexec_b64 s[22:23], vcc
	s_cbranch_execz .LBB0_850
	v_or_b32_e32 v10, v10, v156
	v_lshlrev_b32_e32 v10, 2, v10
	s_waitcnt lgkmcnt(0)
	v_add_f32_e32 v12, v11, v12
	v_ashrrev_i32_e32 v11, 31, v10
	v_lshl_add_u64 v[10:11], v[10:11], 2, s[0:1]
	global_store_dword v[10:11], v12, off
.LBB0_850:
	s_or_b64 exec, exec, s[22:23]
	v_or_b32_e32 v5, 28, v5
	v_lshl_add_u32 v6, v5, 8, v6
	s_waitcnt lgkmcnt(0)
	ds_read_b128 v[10:13], v6
	v_lshlrev_b32_e32 v98, 11, v5
	v_lshl_add_u64 v[2:3], v[2:3], 0, v[98:99]
	s_waitcnt lgkmcnt(0)
	global_store_dwordx4 v[2:3], v[10:13], off
	v_and_b32_e32 v3, 0xffff0000, v10
	v_lshlrev_b32_e32 v2, 16, v10
	v_and_b32_e32 v10, 0xffff0000, v11
	v_mul_f32_e32 v3, v3, v3
	v_lshlrev_b32_e32 v6, 16, v11
	v_fmac_f32_e32 v3, v2, v2
	v_mul_f32_e32 v2, v10, v10
	v_lshlrev_b32_e32 v11, 16, v12
	v_and_b32_e32 v12, 0xffff0000, v12
	v_lshlrev_b32_e32 v14, 16, v13
	v_and_b32_e32 v13, 0xffff0000, v13
	v_fmac_f32_e32 v2, v6, v6
	v_add_f32_e32 v2, v3, v2
	v_mul_f32_e32 v3, v12, v12
	v_mul_f32_e32 v6, v13, v13
	v_fmac_f32_e32 v3, v11, v11
	v_fmac_f32_e32 v6, v14, v14
	v_add_f32_e32 v3, v3, v6
	v_add_f32_e32 v2, v2, v3
	s_nop 1
	v_mov_b32_dpp v3, v2 quad_perm:[1,0,3,2] row_mask:0xf bank_mask:0xf
	s_waitcnt lgkmcnt(0)
	v_add_f32_e32 v2, v2, v3
	s_nop 1
	v_mov_b32_dpp v3, v2 quad_perm:[2,3,0,1] row_mask:0xf bank_mask:0xf
	s_waitcnt lgkmcnt(0)
	v_add_f32_e32 v2, v2, v3
	s_nop 1
	v_mov_b32_dpp v3, v2 row_half_mirror row_mask:0xf bank_mask:0xf
	s_waitcnt lgkmcnt(0)
	v_add_f32_e32 v2, v2, v3
	s_nop 1
	v_mov_b32_dpp v3, v2 row_mirror row_mask:0xf bank_mask:0xf
	s_and_saveexec_b64 s[22:23], vcc
	s_cbranch_execz .LBB0_852
	s_waitcnt lgkmcnt(0)
	v_add_f32_e32 v4, v2, v3
	v_or_b32_e32 v2, v5, v156
	v_lshlrev_b32_e32 v2, 2, v2
	v_ashrrev_i32_e32 v3, 31, v2
	v_lshl_add_u64 v[2:3], v[2:3], 2, s[0:1]
	global_store_dword v[2:3], v4, off

.LBB0_870:
	v_cndmask_b32_e64 v102, v102, v214, s[0:1]
	v_mul_f32_e32 v102, 0xbdd53b94, v102
	v_fmamk_f32 v82, v82, 0x3dd53b94, v102
	v_fmamk_f32 v83, v83, 0x3dd53b94, v102
	v_fmamk_f32 v111, v95, 0x3dd53b94, v102
	v_fmamk_f32 v95, v76, 0x3dd53b94, v102
	v_exp_f32_e32 v76, v82
	v_fmamk_f32 v84, v84, 0x3dd53b94, v102
	v_fmamk_f32 v112, v96, 0x3dd53b94, v102
	v_fmamk_f32 v96, v77, 0x3dd53b94, v102
	v_exp_f32_e32 v77, v83
	v_fmamk_f32 v85, v85, 0x3dd53b94, v102
	v_fmamk_f32 v113, v97, 0x3dd53b94, v102
	v_fmamk_f32 v97, v78, 0x3dd53b94, v102
	v_exp_f32_e32 v78, v84
	v_fmamk_f32 v86, v86, 0x3dd53b94, v102
	v_fmamk_f32 v66, v66, 0x3dd53b94, v102
	v_exp_f32_e32 v82, v85
	v_fmamk_f32 v103, v87, 0x3dd53b94, v102
	v_fmamk_f32 v104, v88, 0x3dd53b94, v102
	v_fmamk_f32 v105, v89, 0x3dd53b94, v102
	v_fmamk_f32 v106, v90, 0x3dd53b94, v102
	v_fmamk_f32 v107, v91, 0x3dd53b94, v102
	v_fmamk_f32 v108, v92, 0x3dd53b94, v102
	v_fmamk_f32 v109, v93, 0x3dd53b94, v102
	v_fmamk_f32 v110, v94, 0x3dd53b94, v102
	v_fmamk_f32 v67, v67, 0x3dd53b94, v102
	v_fmamk_f32 v87, v68, 0x3dd53b94, v102
	v_fmamk_f32 v88, v69, 0x3dd53b94, v102
	v_fmamk_f32 v89, v70, 0x3dd53b94, v102
	v_fmamk_f32 v90, v71, 0x3dd53b94, v102
	v_fmamk_f32 v91, v72, 0x3dd53b94, v102
	v_fmamk_f32 v92, v73, 0x3dd53b94, v102
	v_fmamk_f32 v93, v74, 0x3dd53b94, v102
	v_fmamk_f32 v94, v75, 0x3dd53b94, v102
	v_exp_f32_e32 v83, v86
	v_fmamk_f32 v79, v79, 0x3dd53b94, v102
	v_fmamk_f32 v80, v80, 0x3dd53b94, v102
	v_fmac_f32_e32 v102, 0x3dd53b94, v81
	v_exp_f32_e32 v81, v66
	v_add_f32_e32 v66, 0, v76
	v_exp_f32_e32 v84, v103
	v_add_f32_e32 v66, v77, v66
	v_exp_f32_e32 v85, v104
	v_add_f32_e32 v66, v78, v66
	v_exp_f32_e32 v86, v105
	v_add_f32_e32 v66, v82, v66
	v_exp_f32_e32 v68, v106
	v_add_f32_e32 v66, v83, v66
	v_exp_f32_e32 v69, v107
	v_add_f32_e32 v66, v84, v66
	v_exp_f32_e32 v70, v108
	v_add_f32_e32 v66, v85, v66
	v_exp_f32_e32 v71, v109
	v_add_f32_e32 v66, v86, v66
	v_exp_f32_e32 v72, v110
	v_add_f32_e32 v66, v68, v66
	v_exp_f32_e32 v73, v111
	v_add_f32_e32 v66, v69, v66
	v_exp_f32_e32 v74, v112
	v_add_f32_e32 v66, v70, v66
	v_exp_f32_e32 v75, v113
	v_add_f32_e32 v66, v71, v66
	v_add_f32_e32 v66, v72, v66
	v_exp_f32_e32 v103, v67
	v_add_f32_e32 v66, v73, v66
	v_exp_f32_e32 v87, v87
	v_add_f32_e32 v66, v74, v66
	v_exp_f32_e32 v88, v88
	v_add_f32_e32 v66, v75, v66
	v_exp_f32_e32 v89, v89
	v_add_f32_e32 v66, v81, v66
	v_exp_f32_e32 v90, v90
	v_add_f32_e32 v66, v103, v66
	v_exp_f32_e32 v91, v91
	v_add_f32_e32 v66, v87, v66
	v_exp_f32_e32 v92, v92
	v_add_f32_e32 v66, v88, v66
	v_exp_f32_e32 v93, v93
	v_add_f32_e32 v66, v89, v66
	v_exp_f32_e32 v94, v94
	v_add_f32_e32 v66, v90, v66
	v_exp_f32_e32 v95, v95
	v_add_f32_e32 v66, v91, v66
	v_exp_f32_e32 v96, v96
	v_add_f32_e32 v66, v92, v66
	v_exp_f32_e32 v97, v97
	v_add_f32_e32 v66, v93, v66
	v_exp_f32_e32 v104, v79
	v_add_f32_e32 v66, v94, v66
	v_exp_f32_e32 v105, v80
	v_add_f32_e32 v66, v95, v66
	v_exp_f32_e32 v102, v102
	v_add_f32_e32 v66, v96, v66
	v_add_f32_e32 v66, v97, v66
	v_add_f32_e32 v66, v104, v66
	v_add_f32_e32 v66, v105, v66
	v_add_f32_e32 v66, v102, v66
	v_mov_b32_e32 v67, v66
	v_mov_b32_e32 v201, 0x800
	v_mov_b32_e32 v202, v200
	v_mov_b32_e32 v200, 0x7ff
	v_permlane32_swap_b32_e32 v66, v67
	v_cvt_pk_bf16_f32 v76, v76, v77
	v_cvt_pk_bf16_f32 v77, v78, v82
	v_cvt_pk_bf16_f32 v78, v83, v84
	v_cvt_pk_bf16_f32 v79, v85, v86
	v_cvt_pk_bf16_f32 v68, v68, v69
	v_cvt_pk_bf16_f32 v69, v70, v71
	v_cvt_pk_bf16_f32 v70, v72, v73
	v_cvt_pk_bf16_f32 v71, v74, v75
	v_cvt_pk_bf16_f32 v72, v81, v103
	v_cvt_pk_bf16_f32 v73, v87, v88
	v_cvt_pk_bf16_f32 v74, v89, v90
	v_cvt_pk_bf16_f32 v75, v91, v92
	v_cvt_pk_bf16_f32 v80, v93, v94
	v_cvt_pk_bf16_f32 v81, v95, v96
	v_cvt_pk_bf16_f32 v82, v97, v104
	v_cvt_pk_bf16_f32 v83, v105, v102
	v_permlane32_swap_b32_e32 v76, v78
	v_permlane32_swap_b32_e32 v77, v79
	v_permlane32_swap_b32_e32 v68, v70
	v_permlane32_swap_b32_e32 v69, v71
	v_permlane32_swap_b32_e32 v72, v74
	v_permlane32_swap_b32_e32 v73, v75
	v_permlane32_swap_b32_e32 v80, v82
	v_permlane32_swap_b32_e32 v81, v83
	ds_read_b64_tr_b16 v[84:85], v199 offset:0
	ds_read_b64_tr_b16 v[86:87], v199 offset:0x800
	ds_read_b64_tr_b16 v[88:89], v199 offset:0x1000
	ds_read_b64_tr_b16 v[90:91], v199 offset:0x1800
	ds_read_b64_tr_b16 v[92:93], v199 offset:0x2000
	ds_read_b64_tr_b16 v[94:95], v199 offset:0x2800
	ds_read_b64_tr_b16 v[102:103], v199 offset:0x3000
	ds_read_b64_tr_b16 v[104:105], v199 offset:0x3800
	s_waitcnt lgkmcnt(0)
	s_nop 0
	v_mfma_f32_32x32x16_bf16 v[2:17], v[76:79], v[84:87], v[2:17]
	ds_read_b64_tr_b16 v[84:85], v199 offset:0x200
	ds_read_b64_tr_b16 v[86:87], v199 offset:0xa00
	v_mfma_f32_32x32x16_bf16 v[2:17], v[68:71], v[88:91], v[2:17]
	ds_read_b64_tr_b16 v[88:89], v199 offset:0x1200
	ds_read_b64_tr_b16 v[90:91], v199 offset:0x1a00
	v_mfma_f32_32x32x16_bf16 v[2:17], v[72:75], v[92:95], v[2:17]
	ds_read_b64_tr_b16 v[92:93], v199 offset:0x2200
	ds_read_b64_tr_b16 v[94:95], v199 offset:0x2a00
	v_mfma_f32_32x32x16_bf16 v[2:17], v[80:83], v[102:105], v[2:17]
	ds_read_b64_tr_b16 v[102:103], v199 offset:0x3200
	ds_read_b64_tr_b16 v[104:105], v199 offset:0x3a00
	s_waitcnt lgkmcnt(0)
	v_mfma_f32_32x32x16_bf16 v[50:65], v[76:79], v[84:87], v[50:65]
	ds_read_b64_tr_b16 v[84:85], v199 offset:0x400
	ds_read_b64_tr_b16 v[86:87], v199 offset:0xc00
	v_mfma_f32_32x32x16_bf16 v[50:65], v[68:71], v[88:91], v[50:65]
	ds_read_b64_tr_b16 v[88:89], v199 offset:0x1400
	ds_read_b64_tr_b16 v[90:91], v199 offset:0x1c00
	v_mfma_f32_32x32x16_bf16 v[50:65], v[72:75], v[92:95], v[50:65]
	ds_read_b64_tr_b16 v[92:93], v199 offset:0x2400
	ds_read_b64_tr_b16 v[94:95], v199 offset:0x2c00
	v_mfma_f32_32x32x16_bf16 v[50:65], v[80:83], v[102:105], v[50:65]
	ds_read_b64_tr_b16 v[102:103], v199 offset:0x3400
	ds_read_b64_tr_b16 v[104:105], v199 offset:0x3c00
	s_waitcnt lgkmcnt(0)
	v_mfma_f32_32x32x16_bf16 v[34:49], v[76:79], v[84:87], v[34:49]
	ds_read_b64_tr_b16 v[84:85], v199 offset:0x600
	ds_read_b64_tr_b16 v[86:87], v199 offset:0xe00
	v_mfma_f32_32x32x16_bf16 v[34:49], v[68:71], v[88:91], v[34:49]
	ds_read_b64_tr_b16 v[88:89], v199 offset:0x1600
	ds_read_b64_tr_b16 v[90:91], v199 offset:0x1e00
	v_mfma_f32_32x32x16_bf16 v[34:49], v[72:75], v[92:95], v[34:49]
	ds_read_b64_tr_b16 v[92:93], v199 offset:0x2600
	ds_read_b64_tr_b16 v[94:95], v199 offset:0x2e00
	v_mfma_f32_32x32x16_bf16 v[34:49], v[80:83], v[102:105], v[34:49]
	ds_read_b64_tr_b16 v[102:103], v199 offset:0x3600
	ds_read_b64_tr_b16 v[104:105], v199 offset:0x3e00
	s_waitcnt lgkmcnt(0)
	v_mfma_f32_32x32x16_bf16 v[18:33], v[76:79], v[84:87], v[18:33]
	v_mfma_f32_32x32x16_bf16 v[18:33], v[68:71], v[88:91], v[18:33]
	v_mfma_f32_32x32x16_bf16 v[18:33], v[72:75], v[92:95], v[18:33]
	v_mfma_f32_32x32x16_bf16 v[18:33], v[80:83], v[102:105], v[18:33]
	s_and_saveexec_b64 s[0:1], s[38:39]
	v_add_f32_e32 v68, v98, v100
	v_fmac_f32_e32 v68, v198, v152
	v_add_f32_e32 v66, v66, v67
	v_fmac_f32_e32 v66, v68, v101
	ds_write_b32 v197, v66
	s_or_b64 exec, exec, s[0:1]
	s_waitcnt lgkmcnt(0)
	ds_read_b128 v[66:69], v193
	ds_read_b128 v[70:73], v193 offset:32
	s_lshl_b64 s[0:1], s[42:43], 11
	s_add_u32 s2, s20, s0
	s_addc_u32 s8, s21, s1
	s_lshl_b64 s[0:1], s[42:43], 4
	s_lshl_b32 s7, s7, 1
	s_add_u32 s22, s2, s7
	s_waitcnt lgkmcnt(1)
	v_rcp_f32_e32 v74, v66
	s_addc_u32 s23, s8, 0
	v_readlane_b32 s8, v251, 58
	v_readlane_b32 s9, v251, 59
	s_add_u32 s0, s8, s0
	s_addc_u32 s1, s9, s1
	s_lshl_b32 s2, s4, 2
	s_add_u32 s0, s0, s2
	v_lshl_add_u32 v82, v161, 13, 0
	v_mul_f32_e32 v2, v2, v74
	v_lshlrev_b32_e32 v83, 10, v173
	v_lshlrev_b32_e32 v84, 1, v172
	v_cvt_pk_bf16_f32 v2, v2, s0
	v_add3_u32 v83, v82, v83, v84
	v_rcp_f32_e32 v75, v67
	v_rcp_f32_e32 v76, v68
	v_rcp_f32_e32 v77, v69
	s_waitcnt lgkmcnt(0)
	v_rcp_f32_e32 v78, v70
	ds_read_b128 v[66:69], v193 offset:64
	v_rcp_f32_e32 v79, v71
	v_rcp_f32_e32 v80, v72
	v_rcp_f32_e32 v81, v73
	ds_read_b128 v[70:73], v193 offset:96
	s_waitcnt lgkmcnt(0)
	s_barrier
	ds_write_b16 v83, v2
	v_mul_f32_e32 v2, v50, v74
	v_cvt_pk_bf16_f32 v2, v2, s0
	ds_write_b16 v83, v2 offset:64
	v_mul_f32_e32 v2, v34, v74
	v_cvt_pk_bf16_f32 v2, v2, s0
	ds_write_b16 v83, v2 offset:128
	v_mul_f32_e32 v2, v18, v74
	v_cvt_pk_bf16_f32 v2, v2, s0
	ds_write_b16 v83, v2 offset:192
	v_mul_f32_e32 v2, v3, v75
	v_cvt_pk_bf16_f32 v2, v2, s0
	ds_write_b16 v83, v2 offset:256
	v_mul_f32_e32 v2, v51, v75
	v_cvt_pk_bf16_f32 v2, v2, s0
	ds_write_b16 v83, v2 offset:320
	v_mul_f32_e32 v2, v35, v75
	v_cvt_pk_bf16_f32 v2, v2, s0
	ds_write_b16 v83, v2 offset:384
	v_mul_f32_e32 v2, v19, v75
	v_cvt_pk_bf16_f32 v2, v2, s0
	ds_write_b16 v83, v2 offset:448
	v_mul_f32_e32 v2, v4, v76
	v_cvt_pk_bf16_f32 v2, v2, s0
	ds_write_b16 v83, v2 offset:512
	v_mul_f32_e32 v2, v52, v76
	v_cvt_pk_bf16_f32 v2, v2, s0
	ds_write_b16 v83, v2 offset:576
	v_mul_f32_e32 v2, v36, v76
	v_cvt_pk_bf16_f32 v2, v2, s0
	ds_write_b16 v83, v2 offset:640
	v_mul_f32_e32 v2, v20, v76
	v_cvt_pk_bf16_f32 v2, v2, s0
	ds_write_b16 v83, v2 offset:704
	v_mul_f32_e32 v2, v5, v77
	v_cvt_pk_bf16_f32 v2, v2, s0
	ds_write_b16 v83, v2 offset:768
	v_mul_f32_e32 v2, v53, v77
	v_cvt_pk_bf16_f32 v2, v2, s0
	ds_write_b16 v83, v2 offset:832
	v_mul_f32_e32 v2, v37, v77
	v_cvt_pk_bf16_f32 v2, v2, s0
	ds_write_b16 v83, v2 offset:896
	v_mul_f32_e32 v2, v21, v77
	v_cvt_pk_bf16_f32 v2, v2, s0
	ds_write_b16 v83, v2 offset:960
	v_mul_f32_e32 v2, v6, v78
	v_cvt_pk_bf16_f32 v2, v2, s0
	ds_write_b16 v83, v2 offset:2048
	v_mul_f32_e32 v2, v54, v78
	v_cvt_pk_bf16_f32 v2, v2, s0
	ds_write_b16 v83, v2 offset:2112
	v_mul_f32_e32 v2, v38, v78
	v_cvt_pk_bf16_f32 v2, v2, s0
	ds_write_b16 v83, v2 offset:2176
	v_mul_f32_e32 v2, v22, v78
	v_cvt_pk_bf16_f32 v2, v2, s0
	ds_write_b16 v83, v2 offset:2240
	v_mul_f32_e32 v2, v7, v79
	v_cvt_pk_bf16_f32 v2, v2, s0
	ds_write_b16 v83, v2 offset:2304
	v_mul_f32_e32 v2, v55, v79
	v_cvt_pk_bf16_f32 v2, v2, s0
	ds_write_b16 v83, v2 offset:2368
	v_mul_f32_e32 v2, v39, v79
	v_cvt_pk_bf16_f32 v2, v2, s0
	ds_write_b16 v83, v2 offset:2432
	v_mul_f32_e32 v2, v23, v79
	v_cvt_pk_bf16_f32 v2, v2, s0
	ds_write_b16 v83, v2 offset:2496
	v_mul_f32_e32 v2, v8, v80
	v_cvt_pk_bf16_f32 v2, v2, s0
	ds_write_b16 v83, v2 offset:2560
	v_mul_f32_e32 v2, v56, v80
	v_cvt_pk_bf16_f32 v2, v2, s0
	ds_write_b16 v83, v2 offset:2624
	v_mul_f32_e32 v2, v40, v80
	v_cvt_pk_bf16_f32 v2, v2, s0
	ds_write_b16 v83, v2 offset:2688
	v_mul_f32_e32 v2, v24, v80
	v_cvt_pk_bf16_f32 v2, v2, s0
	ds_write_b16 v83, v2 offset:2752
	v_mul_f32_e32 v2, v9, v81
	v_cvt_pk_bf16_f32 v2, v2, s0
	ds_write_b16 v83, v2 offset:2816
	v_mul_f32_e32 v2, v57, v81
	v_cvt_pk_bf16_f32 v2, v2, s0
	v_rcp_f32_e32 v66, v66
	ds_write_b16 v83, v2 offset:2880
	v_mul_f32_e32 v2, v41, v81
	v_cvt_pk_bf16_f32 v2, v2, s0
	ds_write_b16 v83, v2 offset:2944
	v_mul_f32_e32 v2, v25, v81
	v_cvt_pk_bf16_f32 v2, v2, s0
	ds_write_b16 v83, v2 offset:3008
	v_mul_f32_e32 v2, v10, v66
	v_cvt_pk_bf16_f32 v2, v2, s0
	ds_write_b16 v83, v2 offset:4096
	v_mul_f32_e32 v2, v58, v66
	v_cvt_pk_bf16_f32 v2, v2, s0
	v_rcp_f32_e32 v67, v67
	ds_write_b16 v83, v2 offset:4160
	v_mul_f32_e32 v2, v42, v66
	v_cvt_pk_bf16_f32 v2, v2, s0
	ds_write_b16 v83, v2 offset:4224
	v_mul_f32_e32 v2, v26, v66
	v_cvt_pk_bf16_f32 v2, v2, s0
	ds_write_b16 v83, v2 offset:4288
	v_mul_f32_e32 v2, v11, v67
	v_cvt_pk_bf16_f32 v2, v2, s0
	ds_write_b16 v83, v2 offset:4352
	v_mul_f32_e32 v2, v59, v67
	v_cvt_pk_bf16_f32 v2, v2, s0
	v_rcp_f32_e32 v68, v68
	ds_write_b16 v83, v2 offset:4416
	v_mul_f32_e32 v2, v43, v67
	v_cvt_pk_bf16_f32 v2, v2, s0
	ds_write_b16 v83, v2 offset:4480
	v_mul_f32_e32 v2, v27, v67
	v_cvt_pk_bf16_f32 v2, v2, s0
	ds_write_b16 v83, v2 offset:4544
	v_mul_f32_e32 v2, v12, v68
	v_cvt_pk_bf16_f32 v2, v2, s0
	ds_write_b16 v83, v2 offset:4608
	v_mul_f32_e32 v2, v60, v68
	v_cvt_pk_bf16_f32 v2, v2, s0
	v_rcp_f32_e32 v69, v69
	ds_write_b16 v83, v2 offset:4672
	v_mul_f32_e32 v2, v44, v68
	v_cvt_pk_bf16_f32 v2, v2, s0
	ds_write_b16 v83, v2 offset:4736
	v_mul_f32_e32 v2, v28, v68
	v_cvt_pk_bf16_f32 v2, v2, s0
	ds_write_b16 v83, v2 offset:4800
	v_mul_f32_e32 v2, v13, v69
	v_cvt_pk_bf16_f32 v2, v2, s0
	ds_write_b16 v83, v2 offset:4864
	v_mul_f32_e32 v2, v61, v69
	v_cvt_pk_bf16_f32 v2, v2, s0
	v_rcp_f32_e32 v70, v70
	ds_write_b16 v83, v2 offset:4928
	v_mul_f32_e32 v2, v45, v69
	v_cvt_pk_bf16_f32 v2, v2, s0
	ds_write_b16 v83, v2 offset:4992
	v_mul_f32_e32 v2, v29, v69
	v_cvt_pk_bf16_f32 v2, v2, s0
	ds_write_b16 v83, v2 offset:5056
	v_mul_f32_e32 v2, v14, v70
	v_cvt_pk_bf16_f32 v2, v2, s0
	ds_write_b16 v83, v2 offset:6144
	v_mul_f32_e32 v2, v62, v70
	v_cvt_pk_bf16_f32 v2, v2, s0
	v_rcp_f32_e32 v71, v71
	ds_write_b16 v83, v2 offset:6208
	v_mul_f32_e32 v2, v46, v70
	v_cvt_pk_bf16_f32 v2, v2, s0
	ds_write_b16 v83, v2 offset:6272
	v_mul_f32_e32 v2, v30, v70
	v_cvt_pk_bf16_f32 v2, v2, s0
	ds_write_b16 v83, v2 offset:6336
	v_mul_f32_e32 v2, v15, v71
	v_cvt_pk_bf16_f32 v2, v2, s0
	ds_write_b16 v83, v2 offset:6400
	v_mul_f32_e32 v2, v63, v71
	v_cvt_pk_bf16_f32 v2, v2, s0
	v_rcp_f32_e32 v72, v72
	ds_write_b16 v83, v2 offset:6464
	v_mul_f32_e32 v2, v47, v71
	v_cvt_pk_bf16_f32 v2, v2, s0
	ds_write_b16 v83, v2 offset:6528
	v_mul_f32_e32 v2, v31, v71
	v_cvt_pk_bf16_f32 v2, v2, s0
	ds_write_b16 v83, v2 offset:6592
	v_mul_f32_e32 v2, v16, v72
	v_cvt_pk_bf16_f32 v2, v2, s0
	ds_write_b16 v83, v2 offset:6656
	v_mul_f32_e32 v2, v64, v72
	v_cvt_pk_bf16_f32 v2, v2, s0
	v_rcp_f32_e32 v73, v73
	ds_write_b16 v83, v2 offset:6720
	v_mul_f32_e32 v2, v48, v72
	v_cvt_pk_bf16_f32 v2, v2, s0
	ds_write_b16 v83, v2 offset:6784
	v_mul_f32_e32 v2, v32, v72
	v_cvt_pk_bf16_f32 v2, v2, s0
	ds_write_b16 v83, v2 offset:6848
	v_mul_f32_e32 v2, v17, v73
	v_cvt_pk_bf16_f32 v2, v2, s0
	ds_write_b16 v83, v2 offset:6912
	v_mul_f32_e32 v2, v65, v73
	v_cvt_pk_bf16_f32 v2, v2, s0
	ds_write_b16 v83, v2 offset:6976
	v_mul_f32_e32 v2, v49, v73
	v_cvt_pk_bf16_f32 v2, v2, s0
	ds_write_b16 v83, v2 offset:7040
	v_mul_f32_e32 v2, v33, v73
	v_and_b32_e32 v16, 15, v170
	v_cvt_pk_bf16_f32 v2, v2, s0
	v_lshlrev_b32_e32 v98, 4, v16
	ds_write_b16 v83, v2 offset:7104
	v_lshrrev_b32_e32 v5, 4, v171
	v_add_u32_e32 v6, v82, v98
	s_waitcnt lgkmcnt(0)
	v_lshl_add_u32 v8, v5, 8, v6
	ds_read_b128 v[12:15], v8
	v_and_b32_e32 v7, 64, v1
	v_add_u32_e32 v9, 64, v7
	v_xor_b32_e32 v4, 1, v1
	v_cmp_lt_i32_e32 vcc, v4, v9
	s_waitcnt lgkmcnt(0)
	v_and_b32_e32 v8, 0xffff0000, v12
	v_lshlrev_b32_e32 v7, 16, v12
	v_and_b32_e32 v11, 0xffff0000, v13
	v_mul_f32_e32 v8, v8, v8
	v_lshlrev_b32_e32 v10, 16, v13
	v_fmac_f32_e32 v8, v7, v7
	v_mul_f32_e32 v7, v11, v11
	v_and_b32_e32 v18, 0xffff0000, v14
	v_and_b32_e32 v20, 0xffff0000, v15
	v_fmac_f32_e32 v7, v10, v10
	v_lshlrev_b32_e32 v17, 16, v14
	v_lshlrev_b32_e32 v19, 16, v15
	v_add_f32_e32 v7, v8, v7
	v_mul_f32_e32 v8, v18, v18
	v_mul_f32_e32 v10, v20, v20
	v_fmac_f32_e32 v8, v17, v17
	v_fmac_f32_e32 v10, v19, v19
	v_cndmask_b32_e32 v4, v1, v4, vcc
	v_add_f32_e32 v8, v8, v10
	v_lshlrev_b32_e32 v4, 2, v4
	v_add_f32_e32 v8, v7, v8
	s_nop 1
	v_mov_b32_dpp v10, v8 quad_perm:[1,0,3,2] row_mask:0xf bank_mask:0xf
	v_xor_b32_e32 v7, 2, v1
	v_cmp_lt_i32_e32 vcc, v7, v9
	v_xor_b32_e32 v17, 8, v1
	v_ashrrev_i32_e32 v161, 31, v160
	v_cndmask_b32_e32 v7, v1, v7, vcc
	v_lshlrev_b32_e32 v7, 2, v7
	s_waitcnt lgkmcnt(0)
	v_add_f32_e32 v10, v8, v10
	s_nop 1
	v_mov_b32_dpp v11, v10 quad_perm:[2,3,0,1] row_mask:0xf bank_mask:0xf
	v_xor_b32_e32 v8, 4, v1
	v_cmp_lt_i32_e32 vcc, v8, v9
	v_lshlrev_b64 v[2:3], 11, v[160:161]
	v_lshl_add_u64 v[2:3], s[22:23], 0, v[2:3]
	v_cndmask_b32_e32 v8, v1, v8, vcc
	v_lshlrev_b32_e32 v8, 2, v8
	s_waitcnt lgkmcnt(0)
	v_add_f32_e32 v10, v10, v11
	s_nop 1
	v_mov_b32_dpp v11, v10 row_half_mirror row_mask:0xf bank_mask:0xf
	v_cmp_lt_i32_e32 vcc, v17, v9
	v_lshl_add_u64 v[2:3], v[2:3], 0, v[98:99]
	v_lshlrev_b32_e32 v98, 11, v5
	v_cndmask_b32_e32 v9, v1, v17, vcc
	v_lshlrev_b32_e32 v9, 2, v9
	s_waitcnt lgkmcnt(0)
	v_add_f32_e32 v10, v10, v11
	s_nop 1
	v_mov_b32_dpp v11, v10 row_mirror row_mask:0xf bank_mask:0xf
	s_addc_u32 s1, s1, 0
	v_cmp_eq_u32_e32 vcc, 0, v16
	v_lshl_add_u64 v[16:17], v[2:3], 0, v[98:99]
	global_store_dwordx4 v[16:17], v[12:15], off
	s_and_saveexec_b64 s[22:23], vcc
	s_cbranch_execz .LBB0_874
	s_waitcnt lgkmcnt(0)
	v_add_f32_e32 v12, v10, v11
	v_or_b32_e32 v10, v5, v160
	v_lshlrev_b32_e32 v10, 2, v10
	v_ashrrev_i32_e32 v11, 31, v10
	v_lshl_add_u64 v[10:11], v[10:11], 2, s[0:1]
	global_store_dword v[10:11], v12, off
.LBB0_874:
	s_or_b64 exec, exec, s[22:23]
	v_or_b32_e32 v10, 4, v5
	s_waitcnt lgkmcnt(0)
	v_lshl_add_u32 v11, v10, 8, v6
	ds_read_b128 v[12:15], v11
	v_lshlrev_b32_e32 v98, 11, v10
	v_lshl_add_u64 v[16:17], v[2:3], 0, v[98:99]
	s_waitcnt lgkmcnt(0)
	global_store_dwordx4 v[16:17], v[12:15], off
	v_lshlrev_b32_e32 v11, 16, v12
	s_nop 0
	v_and_b32_e32 v12, 0xffff0000, v12
	v_lshlrev_b32_e32 v16, 16, v13
	v_and_b32_e32 v13, 0xffff0000, v13
	v_mul_f32_e32 v12, v12, v12
	v_fmac_f32_e32 v12, v11, v11
	v_mul_f32_e32 v11, v13, v13
	v_lshlrev_b32_e32 v17, 16, v14
	v_and_b32_e32 v14, 0xffff0000, v14
	v_lshlrev_b32_e32 v18, 16, v15
	v_and_b32_e32 v15, 0xffff0000, v15
	v_fmac_f32_e32 v11, v16, v16
	v_add_f32_e32 v11, v12, v11
	v_mul_f32_e32 v12, v14, v14
	v_mul_f32_e32 v13, v15, v15
	v_fmac_f32_e32 v12, v17, v17
	v_fmac_f32_e32 v13, v18, v18
	v_add_f32_e32 v12, v12, v13
	v_add_f32_e32 v11, v11, v12
	s_nop 1
	v_mov_b32_dpp v12, v11 quad_perm:[1,0,3,2] row_mask:0xf bank_mask:0xf
	s_waitcnt lgkmcnt(0)
	v_add_f32_e32 v11, v11, v12
	s_nop 1
	v_mov_b32_dpp v12, v11 quad_perm:[2,3,0,1] row_mask:0xf bank_mask:0xf
	s_waitcnt lgkmcnt(0)
	v_add_f32_e32 v11, v11, v12
	s_nop 1
	v_mov_b32_dpp v12, v11 row_half_mirror row_mask:0xf bank_mask:0xf
	s_waitcnt lgkmcnt(0)
	v_add_f32_e32 v11, v11, v12
	s_nop 1
	v_mov_b32_dpp v12, v11 row_mirror row_mask:0xf bank_mask:0xf
	s_and_saveexec_b64 s[22:23], vcc
	s_cbranch_execz .LBB0_876
	v_or_b32_e32 v10, v10, v160
	v_lshlrev_b32_e32 v10, 2, v10
	s_waitcnt lgkmcnt(0)
	v_add_f32_e32 v12, v11, v12
	v_ashrrev_i32_e32 v11, 31, v10
	v_lshl_add_u64 v[10:11], v[10:11], 2, s[0:1]
	global_store_dword v[10:11], v12, off
.LBB0_876:
	s_or_b64 exec, exec, s[22:23]
	v_or_b32_e32 v10, 8, v5
	v_lshl_add_u32 v11, v10, 8, v6
	s_waitcnt lgkmcnt(0)
	ds_read_b128 v[12:15], v11
	v_lshlrev_b32_e32 v98, 11, v10
	v_lshl_add_u64 v[16:17], v[2:3], 0, v[98:99]
	s_waitcnt lgkmcnt(0)
	global_store_dwordx4 v[16:17], v[12:15], off
	v_lshlrev_b32_e32 v11, 16, v12
	s_nop 0
	v_and_b32_e32 v12, 0xffff0000, v12
	v_lshlrev_b32_e32 v16, 16, v13
	v_and_b32_e32 v13, 0xffff0000, v13
	v_mul_f32_e32 v12, v12, v12
	v_fmac_f32_e32 v12, v11, v11
	v_mul_f32_e32 v11, v13, v13
	v_lshlrev_b32_e32 v17, 16, v14
	v_and_b32_e32 v14, 0xffff0000, v14
	v_lshlrev_b32_e32 v18, 16, v15
	v_and_b32_e32 v15, 0xffff0000, v15
	v_fmac_f32_e32 v11, v16, v16
	v_add_f32_e32 v11, v12, v11
	v_mul_f32_e32 v12, v14, v14
	v_mul_f32_e32 v13, v15, v15
	v_fmac_f32_e32 v12, v17, v17
	v_fmac_f32_e32 v13, v18, v18
	v_add_f32_e32 v12, v12, v13
	v_add_f32_e32 v11, v11, v12
	s_nop 1
	v_mov_b32_dpp v12, v11 quad_perm:[1,0,3,2] row_mask:0xf bank_mask:0xf
	s_waitcnt lgkmcnt(0)
	v_add_f32_e32 v11, v11, v12
	s_nop 1
	v_mov_b32_dpp v12, v11 quad_perm:[2,3,0,1] row_mask:0xf bank_mask:0xf
	s_waitcnt lgkmcnt(0)
	v_add_f32_e32 v11, v11, v12
	s_nop 1
	v_mov_b32_dpp v12, v11 row_half_mirror row_mask:0xf bank_mask:0xf
	s_waitcnt lgkmcnt(0)
	v_add_f32_e32 v11, v11, v12
	s_nop 1
	v_mov_b32_dpp v12, v11 row_mirror row_mask:0xf bank_mask:0xf
	s_and_saveexec_b64 s[22:23], vcc
	s_cbranch_execz .LBB0_878
	v_or_b32_e32 v10, v10, v160
	v_lshlrev_b32_e32 v10, 2, v10
	s_waitcnt lgkmcnt(0)
	v_add_f32_e32 v12, v11, v12
	v_ashrrev_i32_e32 v11, 31, v10
	v_lshl_add_u64 v[10:11], v[10:11], 2, s[0:1]
	global_store_dword v[10:11], v12, off
.LBB0_878:
	s_or_b64 exec, exec, s[22:23]
	v_or_b32_e32 v10, 12, v5
	v_lshl_add_u32 v11, v10, 8, v6
	s_waitcnt lgkmcnt(0)
	ds_read_b128 v[12:15], v11
	v_lshlrev_b32_e32 v98, 11, v10
	v_lshl_add_u64 v[16:17], v[2:3], 0, v[98:99]
	s_waitcnt lgkmcnt(0)
	global_store_dwordx4 v[16:17], v[12:15], off
	v_lshlrev_b32_e32 v11, 16, v12
	s_nop 0
	v_and_b32_e32 v12, 0xffff0000, v12
	v_lshlrev_b32_e32 v16, 16, v13
	v_and_b32_e32 v13, 0xffff0000, v13
	v_mul_f32_e32 v12, v12, v12
	v_fmac_f32_e32 v12, v11, v11
	v_mul_f32_e32 v11, v13, v13
	v_lshlrev_b32_e32 v17, 16, v14
	v_and_b32_e32 v14, 0xffff0000, v14
	v_lshlrev_b32_e32 v18, 16, v15
	v_and_b32_e32 v15, 0xffff0000, v15
	v_fmac_f32_e32 v11, v16, v16
	v_add_f32_e32 v11, v12, v11
	v_mul_f32_e32 v12, v14, v14
	v_mul_f32_e32 v13, v15, v15
	v_fmac_f32_e32 v12, v17, v17
	v_fmac_f32_e32 v13, v18, v18
	v_add_f32_e32 v12, v12, v13
	v_add_f32_e32 v11, v11, v12
	s_nop 1
	v_mov_b32_dpp v12, v11 quad_perm:[1,0,3,2] row_mask:0xf bank_mask:0xf
	s_waitcnt lgkmcnt(0)
	v_add_f32_e32 v11, v11, v12
	s_nop 1
	v_mov_b32_dpp v12, v11 quad_perm:[2,3,0,1] row_mask:0xf bank_mask:0xf
	s_waitcnt lgkmcnt(0)
	v_add_f32_e32 v11, v11, v12
	s_nop 1
	v_mov_b32_dpp v12, v11 row_half_mirror row_mask:0xf bank_mask:0xf
	s_waitcnt lgkmcnt(0)
	v_add_f32_e32 v11, v11, v12
	s_nop 1
	v_mov_b32_dpp v12, v11 row_mirror row_mask:0xf bank_mask:0xf
	s_and_saveexec_b64 s[22:23], vcc
	s_cbranch_execz .LBB0_880
	v_or_b32_e32 v10, v10, v160
	v_lshlrev_b32_e32 v10, 2, v10
	s_waitcnt lgkmcnt(0)
	v_add_f32_e32 v12, v11, v12
	v_ashrrev_i32_e32 v11, 31, v10
	v_lshl_add_u64 v[10:11], v[10:11], 2, s[0:1]
	global_store_dword v[10:11], v12, off
.LBB0_880:
	s_or_b64 exec, exec, s[22:23]
	v_or_b32_e32 v10, 16, v5
	v_lshl_add_u32 v11, v10, 8, v6
	s_waitcnt lgkmcnt(0)
	ds_read_b128 v[12:15], v11
	v_lshlrev_b32_e32 v98, 11, v10
	v_lshl_add_u64 v[16:17], v[2:3], 0, v[98:99]
	s_waitcnt lgkmcnt(0)
	global_store_dwordx4 v[16:17], v[12:15], off
	v_lshlrev_b32_e32 v11, 16, v12
	s_nop 0
	v_and_b32_e32 v12, 0xffff0000, v12
	v_lshlrev_b32_e32 v16, 16, v13
	v_and_b32_e32 v13, 0xffff0000, v13
	v_mul_f32_e32 v12, v12, v12
	v_fmac_f32_e32 v12, v11, v11
	v_mul_f32_e32 v11, v13, v13
	v_lshlrev_b32_e32 v17, 16, v14
	v_and_b32_e32 v14, 0xffff0000, v14
	v_lshlrev_b32_e32 v18, 16, v15
	v_and_b32_e32 v15, 0xffff0000, v15
	v_fmac_f32_e32 v11, v16, v16
	v_add_f32_e32 v11, v12, v11
	v_mul_f32_e32 v12, v14, v14
	v_mul_f32_e32 v13, v15, v15
	v_fmac_f32_e32 v12, v17, v17
	v_fmac_f32_e32 v13, v18, v18
	v_add_f32_e32 v12, v12, v13
	v_add_f32_e32 v11, v11, v12
	s_nop 1
	v_mov_b32_dpp v12, v11 quad_perm:[1,0,3,2] row_mask:0xf bank_mask:0xf
	s_waitcnt lgkmcnt(0)
	v_add_f32_e32 v11, v11, v12
	s_nop 1
	v_mov_b32_dpp v12, v11 quad_perm:[2,3,0,1] row_mask:0xf bank_mask:0xf
	s_waitcnt lgkmcnt(0)
	v_add_f32_e32 v11, v11, v12
	s_nop 1
	v_mov_b32_dpp v12, v11 row_half_mirror row_mask:0xf bank_mask:0xf
	s_waitcnt lgkmcnt(0)
	v_add_f32_e32 v11, v11, v12
	s_nop 1
	v_mov_b32_dpp v12, v11 row_mirror row_mask:0xf bank_mask:0xf
	s_and_saveexec_b64 s[22:23], vcc
	s_cbranch_execz .LBB0_882
	v_or_b32_e32 v10, v10, v160
	v_lshlrev_b32_e32 v10, 2, v10
	s_waitcnt lgkmcnt(0)
	v_add_f32_e32 v12, v11, v12
	v_ashrrev_i32_e32 v11, 31, v10
	v_lshl_add_u64 v[10:11], v[10:11], 2, s[0:1]
	global_store_dword v[10:11], v12, off
.LBB0_882:
	s_or_b64 exec, exec, s[22:23]
	v_or_b32_e32 v10, 20, v5
	v_lshl_add_u32 v11, v10, 8, v6
	s_waitcnt lgkmcnt(0)
	ds_read_b128 v[12:15], v11
	v_lshlrev_b32_e32 v98, 11, v10
	v_lshl_add_u64 v[16:17], v[2:3], 0, v[98:99]
	s_waitcnt lgkmcnt(0)
	global_store_dwordx4 v[16:17], v[12:15], off
	v_lshlrev_b32_e32 v11, 16, v12
	s_nop 0
	v_and_b32_e32 v12, 0xffff0000, v12
	v_lshlrev_b32_e32 v16, 16, v13
	v_and_b32_e32 v13, 0xffff0000, v13
	v_mul_f32_e32 v12, v12, v12
	v_fmac_f32_e32 v12, v11, v11
	v_mul_f32_e32 v11, v13, v13
	v_lshlrev_b32_e32 v17, 16, v14
	v_and_b32_e32 v14, 0xffff0000, v14
	v_lshlrev_b32_e32 v18, 16, v15
	v_and_b32_e32 v15, 0xffff0000, v15
	v_fmac_f32_e32 v11, v16, v16
	v_add_f32_e32 v11, v12, v11
	v_mul_f32_e32 v12, v14, v14
	v_mul_f32_e32 v13, v15, v15
	v_fmac_f32_e32 v12, v17, v17
	v_fmac_f32_e32 v13, v18, v18
	v_add_f32_e32 v12, v12, v13
	v_add_f32_e32 v11, v11, v12
	s_nop 1
	v_mov_b32_dpp v12, v11 quad_perm:[1,0,3,2] row_mask:0xf bank_mask:0xf
	s_waitcnt lgkmcnt(0)
	v_add_f32_e32 v11, v11, v12
	s_nop 1
	v_mov_b32_dpp v12, v11 quad_perm:[2,3,0,1] row_mask:0xf bank_mask:0xf
	s_waitcnt lgkmcnt(0)
	v_add_f32_e32 v11, v11, v12
	s_nop 1
	v_mov_b32_dpp v12, v11 row_half_mirror row_mask:0xf bank_mask:0xf
	s_waitcnt lgkmcnt(0)
	v_add_f32_e32 v11, v11, v12
	s_nop 1
	v_mov_b32_dpp v12, v11 row_mirror row_mask:0xf bank_mask:0xf
	s_and_saveexec_b64 s[22:23], vcc
	s_cbranch_execz .LBB0_884
	v_or_b32_e32 v10, v10, v160
	v_lshlrev_b32_e32 v10, 2, v10
	s_waitcnt lgkmcnt(0)
	v_add_f32_e32 v12, v11, v12
	v_ashrrev_i32_e32 v11, 31, v10
	v_lshl_add_u64 v[10:11], v[10:11], 2, s[0:1]
	global_store_dword v[10:11], v12, off
.LBB0_884:
	s_or_b64 exec, exec, s[22:23]
	v_or_b32_e32 v10, 24, v5
	v_lshl_add_u32 v11, v10, 8, v6
	s_waitcnt lgkmcnt(0)
	ds_read_b128 v[12:15], v11
	v_lshlrev_b32_e32 v98, 11, v10
	v_lshl_add_u64 v[16:17], v[2:3], 0, v[98:99]
	s_waitcnt lgkmcnt(0)
	global_store_dwordx4 v[16:17], v[12:15], off
	v_lshlrev_b32_e32 v11, 16, v12
	s_nop 0
	v_and_b32_e32 v12, 0xffff0000, v12
	v_lshlrev_b32_e32 v16, 16, v13
	v_and_b32_e32 v13, 0xffff0000, v13
	v_mul_f32_e32 v12, v12, v12
	v_fmac_f32_e32 v12, v11, v11
	v_mul_f32_e32 v11, v13, v13
	v_lshlrev_b32_e32 v17, 16, v14
	v_and_b32_e32 v14, 0xffff0000, v14
	v_lshlrev_b32_e32 v18, 16, v15
	v_and_b32_e32 v15, 0xffff0000, v15
	v_fmac_f32_e32 v11, v16, v16
	v_add_f32_e32 v11, v12, v11
	v_mul_f32_e32 v12, v14, v14
	v_mul_f32_e32 v13, v15, v15
	v_fmac_f32_e32 v12, v17, v17
	v_fmac_f32_e32 v13, v18, v18
	v_add_f32_e32 v12, v12, v13
	v_add_f32_e32 v11, v11, v12
	s_nop 1
	v_mov_b32_dpp v12, v11 quad_perm:[1,0,3,2] row_mask:0xf bank_mask:0xf
	s_waitcnt lgkmcnt(0)
	v_add_f32_e32 v11, v11, v12
	s_nop 1
	v_mov_b32_dpp v12, v11 quad_perm:[2,3,0,1] row_mask:0xf bank_mask:0xf
	s_waitcnt lgkmcnt(0)
	v_add_f32_e32 v11, v11, v12
	s_nop 1
	v_mov_b32_dpp v12, v11 row_half_mirror row_mask:0xf bank_mask:0xf
	s_waitcnt lgkmcnt(0)
	v_add_f32_e32 v11, v11, v12
	s_nop 1
	v_mov_b32_dpp v12, v11 row_mirror row_mask:0xf bank_mask:0xf
	s_and_saveexec_b64 s[22:23], vcc
	s_cbranch_execz .LBB0_886
	v_or_b32_e32 v10, v10, v160
	v_lshlrev_b32_e32 v10, 2, v10
	s_waitcnt lgkmcnt(0)
	v_add_f32_e32 v12, v11, v12
	v_ashrrev_i32_e32 v11, 31, v10
	v_lshl_add_u64 v[10:11], v[10:11], 2, s[0:1]
	global_store_dword v[10:11], v12, off
.LBB0_886:
	s_or_b64 exec, exec, s[22:23]
	v_or_b32_e32 v5, 28, v5
	v_lshl_add_u32 v6, v5, 8, v6
	s_waitcnt lgkmcnt(0)
	ds_read_b128 v[10:13], v6
	v_lshlrev_b32_e32 v98, 11, v5
	v_lshl_add_u64 v[2:3], v[2:3], 0, v[98:99]
	s_waitcnt lgkmcnt(0)
	global_store_dwordx4 v[2:3], v[10:13], off
	v_and_b32_e32 v3, 0xffff0000, v10
	v_lshlrev_b32_e32 v2, 16, v10
	v_and_b32_e32 v10, 0xffff0000, v11
	v_mul_f32_e32 v3, v3, v3
	v_lshlrev_b32_e32 v6, 16, v11
	v_fmac_f32_e32 v3, v2, v2
	v_mul_f32_e32 v2, v10, v10
	v_lshlrev_b32_e32 v11, 16, v12
	v_and_b32_e32 v12, 0xffff0000, v12
	v_lshlrev_b32_e32 v14, 16, v13
	v_and_b32_e32 v13, 0xffff0000, v13
	v_fmac_f32_e32 v2, v6, v6
	v_add_f32_e32 v2, v3, v2
	v_mul_f32_e32 v3, v12, v12
	v_mul_f32_e32 v6, v13, v13
	v_fmac_f32_e32 v3, v11, v11
	v_fmac_f32_e32 v6, v14, v14
	v_add_f32_e32 v3, v3, v6
	v_add_f32_e32 v2, v2, v3
	s_nop 1
	v_mov_b32_dpp v3, v2 quad_perm:[1,0,3,2] row_mask:0xf bank_mask:0xf
	s_waitcnt lgkmcnt(0)
	v_add_f32_e32 v2, v2, v3
	s_nop 1
	v_mov_b32_dpp v3, v2 quad_perm:[2,3,0,1] row_mask:0xf bank_mask:0xf
	s_waitcnt lgkmcnt(0)
	v_add_f32_e32 v2, v2, v3
	s_nop 1
	v_mov_b32_dpp v3, v2 row_half_mirror row_mask:0xf bank_mask:0xf
	s_waitcnt lgkmcnt(0)
	v_add_f32_e32 v2, v2, v3
	s_nop 1
	v_mov_b32_dpp v3, v2 row_mirror row_mask:0xf bank_mask:0xf
	s_and_saveexec_b64 s[22:23], vcc
	s_cbranch_execz .LBB0_819
	s_waitcnt lgkmcnt(0)
	v_add_f32_e32 v4, v2, v3
	v_or_b32_e32 v2, v5, v160
	v_lshlrev_b32_e32 v2, 2, v2
	v_ashrrev_i32_e32 v3, 31, v2
	v_lshl_add_u64 v[2:3], v[2:3], 2, s[0:1]
	global_store_dword v[2:3], v4, off
	s_branch .LBB0_819
